# PLE GEMM in P3b; 35840 conversion items (32/wave) deferred into P1 tail
# speedup vs baseline: 1.0042x; 1.0042x over previous
.LBB0_9:
	s_cmp_lg_u32 s101, 0
	s_cbranch_scc1 .Lcv_go
	s_cmp_lt_i32 s80, 0x11e80
	s_cbranch_scc1 .Lcv_go
	s_cmp_lt_i32 s80, 0x1aa80
	s_cbranch_scc1 .LBB0_8

.LBB0_399:
	s_cmpk_eq_i32 s88, 0x100
	s_cselect_b64 s[0:1], -1, 0
	s_cmpk_lg_i32 s88, 0x100
	v_writelane_b32 v250, s0, 23
	s_cselect_b64 s[22:23], -1, 0
	s_cmpk_lt_i32 s2, 0x74
	v_writelane_b32 v250, s1, 24
	s_cselect_b64 s[0:1], -1, 0
	s_or_b64 s[0:1], s[0:1], s[22:23]
	s_and_b64 vcc, exec, s[0:1]
	s_cbranch_vccnz .LBB0_416
	v_writelane_b32 v248, s0, 0
	v_writelane_b32 v248, s1, 1
	v_writelane_b32 v248, s2, 2
	v_writelane_b32 v248, s3, 3
	v_writelane_b32 v248, s4, 4
	v_writelane_b32 v248, s5, 5
	v_writelane_b32 v248, s6, 6
	v_writelane_b32 v248, s7, 7
	v_writelane_b32 v248, s8, 8
	v_writelane_b32 v248, s9, 9
	v_writelane_b32 v248, s10, 10
	v_writelane_b32 v248, s11, 11
	v_writelane_b32 v248, s12, 12
	v_writelane_b32 v248, s13, 13
	v_writelane_b32 v248, s14, 14
	v_writelane_b32 v248, s15, 15
	v_writelane_b32 v248, s16, 16
	v_writelane_b32 v248, s17, 17
	v_writelane_b32 v248, s18, 18
	v_writelane_b32 v248, s19, 19
	v_writelane_b32 v248, s20, 20
	v_writelane_b32 v248, s21, 21
	v_writelane_b32 v248, s22, 22
	v_writelane_b32 v248, s23, 23
	v_writelane_b32 v248, s24, 24
	v_writelane_b32 v248, s25, 25
	v_writelane_b32 v248, s26, 26
	v_writelane_b32 v248, s27, 27
	v_writelane_b32 v248, s28, 28
	v_writelane_b32 v248, s29, 29
	v_writelane_b32 v248, s30, 30
	v_writelane_b32 v248, s31, 31
	v_writelane_b32 v248, s32, 32
	v_writelane_b32 v248, s33, 33
	v_writelane_b32 v248, s34, 34
	v_writelane_b32 v248, s35, 35
	v_writelane_b32 v248, s36, 36
	v_writelane_b32 v248, s37, 37
	v_writelane_b32 v248, s38, 38
	v_writelane_b32 v248, s39, 39
	v_writelane_b32 v248, s40, 40
	v_writelane_b32 v248, s41, 41
	v_writelane_b32 v248, s42, 42
	v_writelane_b32 v248, s43, 43
	v_writelane_b32 v248, s44, 44
	v_writelane_b32 v248, s45, 45
	v_writelane_b32 v248, s46, 46
	v_writelane_b32 v248, s47, 47
	v_writelane_b32 v248, s48, 48
	v_writelane_b32 v248, s49, 49
	v_writelane_b32 v248, s50, 50
	v_writelane_b32 v248, s51, 51
	v_writelane_b32 v248, s52, 52
	v_writelane_b32 v248, s53, 53
	v_writelane_b32 v248, s54, 54
	v_writelane_b32 v248, s55, 55
	v_writelane_b32 v248, s56, 56
	v_writelane_b32 v248, s57, 57
	v_writelane_b32 v248, s58, 58
	v_writelane_b32 v248, s59, 59
	v_writelane_b32 v248, s60, 60
	v_writelane_b32 v248, s61, 61
	v_writelane_b32 v248, s62, 62
	v_writelane_b32 v248, s63, 63
	v_writelane_b32 v249, s64, 0
	v_writelane_b32 v249, s65, 1
	v_writelane_b32 v249, s66, 2
	v_writelane_b32 v249, s67, 3
	v_writelane_b32 v249, s68, 4
	v_writelane_b32 v249, s69, 5
	v_writelane_b32 v249, s70, 6
	v_writelane_b32 v249, s71, 7
	v_writelane_b32 v249, s72, 8
	v_writelane_b32 v249, s73, 9
	v_writelane_b32 v249, s74, 10
	v_writelane_b32 v249, s75, 11
	v_writelane_b32 v249, s76, 12
	v_writelane_b32 v249, s77, 13
	v_writelane_b32 v249, s78, 14
	v_writelane_b32 v249, s79, 15
	v_writelane_b32 v249, s80, 16
	v_writelane_b32 v249, s81, 17
	v_writelane_b32 v249, s82, 18
	v_writelane_b32 v249, s83, 19
	v_writelane_b32 v249, s84, 20
	v_writelane_b32 v249, s85, 21
	v_writelane_b32 v249, s86, 22
	v_writelane_b32 v249, s87, 23
	v_writelane_b32 v249, s88, 24
	v_writelane_b32 v249, s89, 25
	v_writelane_b32 v249, s90, 26
	v_writelane_b32 v249, s91, 27
	v_writelane_b32 v249, s92, 28
	v_writelane_b32 v249, s93, 29
	v_writelane_b32 v249, s94, 30
	v_writelane_b32 v249, s95, 31
	v_writelane_b32 v249, s96, 32
	v_writelane_b32 v249, s97, 33
	v_readlane_b32 s1, v250, 9
	v_readlane_b32 s86, v250, 10
	v_readlane_b32 s87, v250, 11
	s_sub_i32 s0, s2, 0x74
	s_lshl_b32 s0, s0, 3
	s_nop 1
	s_add_i32 s12, s0, s1
	s_add_i32 s12, s12, 0x11e80
	s_movk_i32 s14, 0x460
	s_mov_b32 s100, 0x1aa80
	s_mov_b32 s101, 1
	s_branch .Lcv_entry
